# FFN-up epilogue: gate/val halves n=0 and n=1 computed per 16-row group and written with one 16-byte store per lane instead of two 8-byte stores
# baseline (speedup 1.0000x reference)
.Lffn_nz:
	s_waitcnt vmcnt(8)
	v_pk_fma_f32 v[230:231], v[156:157], v[214:215], v[222:223]
	v_pk_fma_f32 v[234:235], v[152:153], v[218:219], v[226:227]
	v_pk_fma_f32 v[232:233], v[158:159], v[216:217], v[224:225]
	v_pk_fma_f32 v[236:237], v[154:155], v[220:221], v[228:229]
	v_fmac_f32_dpp v230, v156, v206 row_shr:1 row_mask:0xf bank_mask:0xf
	v_fmac_f32_dpp v231, v157, v207 row_shr:1 row_mask:0xf bank_mask:0xf
	v_fmac_f32_dpp v232, v158, v208 row_shr:1 row_mask:0xf bank_mask:0xf
	v_fmac_f32_dpp v233, v159, v209 row_shr:1 row_mask:0xf bank_mask:0xf
	v_fmac_f32_dpp v234, v152, v210 row_shr:1 row_mask:0xf bank_mask:0xf
	v_fmac_f32_dpp v235, v153, v211 row_shr:1 row_mask:0xf bank_mask:0xf
	v_fmac_f32_dpp v236, v154, v212 row_shr:1 row_mask:0xf bank_mask:0xf
	v_fmac_f32_dpp v237, v155, v213 row_shr:1 row_mask:0xf bank_mask:0xf
	v_fmac_f32_dpp v230, v156, v198 row_shr:2 row_mask:0xf bank_mask:0xf
	v_fmac_f32_dpp v231, v157, v199 row_shr:2 row_mask:0xf bank_mask:0xf
	v_fmac_f32_dpp v232, v158, v200 row_shr:2 row_mask:0xf bank_mask:0xf
	v_fmac_f32_dpp v233, v159, v201 row_shr:2 row_mask:0xf bank_mask:0xf
	v_fmac_f32_dpp v234, v152, v202 row_shr:2 row_mask:0xf bank_mask:0xf
	v_fmac_f32_dpp v235, v153, v203 row_shr:2 row_mask:0xf bank_mask:0xf
	v_fmac_f32_dpp v236, v154, v204 row_shr:2 row_mask:0xf bank_mask:0xf
	v_fmac_f32_dpp v237, v155, v205 row_shr:2 row_mask:0xf bank_mask:0xf
	v_pk_mul_f32 v[238:239], v[230:231], v[230:231]
	v_pk_mul_f32 v[240:241], v[232:233], v[232:233]
	v_pk_fma_f32 v[238:239], v[238:239], v[248:249], v[246:247]
	v_pk_fma_f32 v[240:241], v[240:241], v[248:249], v[246:247]
	v_pk_mul_f32 v[238:239], v[230:231], v[238:239]
	v_pk_mul_f32 v[240:241], v[232:233], v[240:241]
	v_exp_f32_e32 v238, v238
	v_exp_f32_e32 v239, v239
	v_exp_f32_e32 v240, v240
	v_exp_f32_e32 v241, v241
	v_pk_add_f32 v[238:239], v[238:239], 1.0 op_sel_hi:[1,0]
	v_pk_add_f32 v[240:241], v[240:241], 1.0 op_sel_hi:[1,0]
	v_rcp_f32_e32 v238, v238
	v_rcp_f32_e32 v239, v239
	v_rcp_f32_e32 v240, v240
	v_rcp_f32_e32 v241, v241
	v_pk_mul_f32 v[230:231], v[230:231], v[234:235]
	v_pk_mul_f32 v[232:233], v[232:233], v[236:237]
	v_pk_mul_f32 v[238:239], v[230:231], v[238:239]
	v_pk_mul_f32 v[240:241], v[232:233], v[240:241]
	v_cvt_pk_bf16_f32 v176, v238, v239
	v_cvt_pk_bf16_f32 v177, v240, v241
	s_waitcnt vmcnt(0)
	v_pk_fma_f32 v[230:231], v[60:61], v[128:129], v[100:101]
	v_pk_fma_f32 v[234:235], v[56:57], v[132:133], v[104:105]
	v_pk_fma_f32 v[232:233], v[62:63], v[130:131], v[102:103]
	v_pk_fma_f32 v[236:237], v[58:59], v[134:135], v[106:107]
	v_fmac_f32_dpp v230, v60, v120 row_shr:1 row_mask:0xf bank_mask:0xf
	v_fmac_f32_dpp v231, v61, v121 row_shr:1 row_mask:0xf bank_mask:0xf
	v_fmac_f32_dpp v232, v62, v122 row_shr:1 row_mask:0xf bank_mask:0xf
	v_fmac_f32_dpp v233, v63, v123 row_shr:1 row_mask:0xf bank_mask:0xf
	v_fmac_f32_dpp v234, v56, v124 row_shr:1 row_mask:0xf bank_mask:0xf
	v_fmac_f32_dpp v235, v57, v125 row_shr:1 row_mask:0xf bank_mask:0xf
	v_fmac_f32_dpp v236, v58, v126 row_shr:1 row_mask:0xf bank_mask:0xf
	v_fmac_f32_dpp v237, v59, v127 row_shr:1 row_mask:0xf bank_mask:0xf
	v_fmac_f32_dpp v230, v60, v112 row_shr:2 row_mask:0xf bank_mask:0xf
	v_fmac_f32_dpp v231, v61, v113 row_shr:2 row_mask:0xf bank_mask:0xf
	v_fmac_f32_dpp v232, v62, v114 row_shr:2 row_mask:0xf bank_mask:0xf
	v_fmac_f32_dpp v233, v63, v115 row_shr:2 row_mask:0xf bank_mask:0xf
	v_fmac_f32_dpp v234, v56, v116 row_shr:2 row_mask:0xf bank_mask:0xf
	v_fmac_f32_dpp v235, v57, v117 row_shr:2 row_mask:0xf bank_mask:0xf
	v_fmac_f32_dpp v236, v58, v118 row_shr:2 row_mask:0xf bank_mask:0xf
	v_fmac_f32_dpp v237, v59, v119 row_shr:2 row_mask:0xf bank_mask:0xf
	v_pk_mul_f32 v[238:239], v[230:231], v[230:231]
	v_pk_mul_f32 v[240:241], v[232:233], v[232:233]
	v_pk_fma_f32 v[238:239], v[238:239], v[248:249], v[246:247]
	v_pk_fma_f32 v[240:241], v[240:241], v[248:249], v[246:247]
	v_pk_mul_f32 v[238:239], v[230:231], v[238:239]
	v_pk_mul_f32 v[240:241], v[232:233], v[240:241]
	v_exp_f32_e32 v238, v238
	v_exp_f32_e32 v239, v239
	v_exp_f32_e32 v240, v240
	v_exp_f32_e32 v241, v241
	v_pk_add_f32 v[238:239], v[238:239], 1.0 op_sel_hi:[1,0]
	v_pk_add_f32 v[240:241], v[240:241], 1.0 op_sel_hi:[1,0]
	v_rcp_f32_e32 v238, v238
	v_rcp_f32_e32 v239, v239
	v_rcp_f32_e32 v240, v240
	v_rcp_f32_e32 v241, v241
	v_pk_mul_f32 v[230:231], v[230:231], v[234:235]
	v_pk_mul_f32 v[232:233], v[232:233], v[236:237]
	v_pk_mul_f32 v[238:239], v[230:231], v[238:239]
	v_pk_mul_f32 v[240:241], v[232:233], v[240:241]
	v_cvt_pk_bf16_f32 v178, v238, v239
	v_cvt_pk_bf16_f32 v179, v240, v241
	s_movk_i32 s15, 0x1002
	v_cmp_gt_i32_e64 s[24:25], s15, v251
	s_sub_u32 s84, s58, 0x2c00
	s_subb_u32 s85, s59, 0
	s_and_b64 s[24:25], s[24:25], s[4:5]
	s_mov_b64 exec, s[24:25]
	global_store_dwordx4 v250, v[176:179], s[84:85]
	s_mov_b64 exec, -1
	s_nop 1
	v_pk_fma_f32 v[230:231], v[148:149], v[214:215], v[222:223]
	v_pk_fma_f32 v[234:235], v[144:145], v[218:219], v[226:227]
	v_pk_fma_f32 v[232:233], v[150:151], v[216:217], v[224:225]
	v_pk_fma_f32 v[236:237], v[146:147], v[220:221], v[228:229]
	v_fmac_f32_dpp v230, v148, v206 row_shr:1 row_mask:0xf bank_mask:0xf
	v_fmac_f32_dpp v231, v149, v207 row_shr:1 row_mask:0xf bank_mask:0xf
	v_fmac_f32_dpp v232, v150, v208 row_shr:1 row_mask:0xf bank_mask:0xf
	v_fmac_f32_dpp v233, v151, v209 row_shr:1 row_mask:0xf bank_mask:0xf
	v_fmac_f32_dpp v234, v144, v210 row_shr:1 row_mask:0xf bank_mask:0xf
	v_fmac_f32_dpp v235, v145, v211 row_shr:1 row_mask:0xf bank_mask:0xf
	v_fmac_f32_dpp v236, v146, v212 row_shr:1 row_mask:0xf bank_mask:0xf
	v_fmac_f32_dpp v237, v147, v213 row_shr:1 row_mask:0xf bank_mask:0xf
	v_fmac_f32_dpp v230, v148, v198 row_shr:2 row_mask:0xf bank_mask:0xf
	v_fmac_f32_dpp v231, v149, v199 row_shr:2 row_mask:0xf bank_mask:0xf
	v_fmac_f32_dpp v232, v150, v200 row_shr:2 row_mask:0xf bank_mask:0xf
	v_fmac_f32_dpp v233, v151, v201 row_shr:2 row_mask:0xf bank_mask:0xf
	v_fmac_f32_dpp v234, v144, v202 row_shr:2 row_mask:0xf bank_mask:0xf
	v_fmac_f32_dpp v235, v145, v203 row_shr:2 row_mask:0xf bank_mask:0xf
	v_fmac_f32_dpp v236, v146, v204 row_shr:2 row_mask:0xf bank_mask:0xf
	v_fmac_f32_dpp v237, v147, v205 row_shr:2 row_mask:0xf bank_mask:0xf
	v_fmac_f32_dpp v230, v156, v206 row_shl:15 row_mask:0xf bank_mask:0xf
	v_fmac_f32_dpp v231, v157, v207 row_shl:15 row_mask:0xf bank_mask:0xf
	v_fmac_f32_dpp v232, v158, v208 row_shl:15 row_mask:0xf bank_mask:0xf
	v_fmac_f32_dpp v233, v159, v209 row_shl:15 row_mask:0xf bank_mask:0xf
	v_fmac_f32_dpp v234, v152, v210 row_shl:15 row_mask:0xf bank_mask:0xf
	v_fmac_f32_dpp v235, v153, v211 row_shl:15 row_mask:0xf bank_mask:0xf
	v_fmac_f32_dpp v236, v154, v212 row_shl:15 row_mask:0xf bank_mask:0xf
	v_fmac_f32_dpp v237, v155, v213 row_shl:15 row_mask:0xf bank_mask:0xf
	v_fmac_f32_dpp v230, v156, v198 row_shl:14 row_mask:0xf bank_mask:0xf
	v_fmac_f32_dpp v231, v157, v199 row_shl:14 row_mask:0xf bank_mask:0xf
	v_fmac_f32_dpp v232, v158, v200 row_shl:14 row_mask:0xf bank_mask:0xf
	v_fmac_f32_dpp v233, v159, v201 row_shl:14 row_mask:0xf bank_mask:0xf
	v_fmac_f32_dpp v234, v152, v202 row_shl:14 row_mask:0xf bank_mask:0xf
	v_fmac_f32_dpp v235, v153, v203 row_shl:14 row_mask:0xf bank_mask:0xf
	v_fmac_f32_dpp v236, v154, v204 row_shl:14 row_mask:0xf bank_mask:0xf
	v_fmac_f32_dpp v237, v155, v205 row_shl:14 row_mask:0xf bank_mask:0xf
	v_pk_mul_f32 v[238:239], v[230:231], v[230:231]
	v_pk_mul_f32 v[240:241], v[232:233], v[232:233]
	v_pk_fma_f32 v[238:239], v[238:239], v[248:249], v[246:247]
	v_pk_fma_f32 v[240:241], v[240:241], v[248:249], v[246:247]
	v_pk_mul_f32 v[238:239], v[230:231], v[238:239]
	v_pk_mul_f32 v[240:241], v[232:233], v[240:241]
	v_exp_f32_e32 v238, v238
	v_exp_f32_e32 v239, v239
	v_exp_f32_e32 v240, v240
	v_exp_f32_e32 v241, v241
	v_pk_add_f32 v[238:239], v[238:239], 1.0 op_sel_hi:[1,0]
	v_pk_add_f32 v[240:241], v[240:241], 1.0 op_sel_hi:[1,0]
	v_rcp_f32_e32 v238, v238
	v_rcp_f32_e32 v239, v239
	v_rcp_f32_e32 v240, v240
	v_rcp_f32_e32 v241, v241
	v_pk_mul_f32 v[230:231], v[230:231], v[234:235]
	v_pk_mul_f32 v[232:233], v[232:233], v[236:237]
	v_pk_mul_f32 v[238:239], v[230:231], v[238:239]
	v_pk_mul_f32 v[240:241], v[232:233], v[240:241]
	v_cvt_pk_bf16_f32 v180, v238, v239
	v_cvt_pk_bf16_f32 v181, v240, v241
	v_pk_fma_f32 v[230:231], v[52:53], v[128:129], v[100:101]
	v_pk_fma_f32 v[234:235], v[48:49], v[132:133], v[104:105]
	v_pk_fma_f32 v[232:233], v[54:55], v[130:131], v[102:103]
	v_pk_fma_f32 v[236:237], v[50:51], v[134:135], v[106:107]
	v_fmac_f32_dpp v230, v52, v120 row_shr:1 row_mask:0xf bank_mask:0xf
	v_fmac_f32_dpp v231, v53, v121 row_shr:1 row_mask:0xf bank_mask:0xf
	v_fmac_f32_dpp v232, v54, v122 row_shr:1 row_mask:0xf bank_mask:0xf
	v_fmac_f32_dpp v233, v55, v123 row_shr:1 row_mask:0xf bank_mask:0xf
	v_fmac_f32_dpp v234, v48, v124 row_shr:1 row_mask:0xf bank_mask:0xf
	v_fmac_f32_dpp v235, v49, v125 row_shr:1 row_mask:0xf bank_mask:0xf
	v_fmac_f32_dpp v236, v50, v126 row_shr:1 row_mask:0xf bank_mask:0xf
	v_fmac_f32_dpp v237, v51, v127 row_shr:1 row_mask:0xf bank_mask:0xf
	v_fmac_f32_dpp v230, v52, v112 row_shr:2 row_mask:0xf bank_mask:0xf
	v_fmac_f32_dpp v231, v53, v113 row_shr:2 row_mask:0xf bank_mask:0xf
	v_fmac_f32_dpp v232, v54, v114 row_shr:2 row_mask:0xf bank_mask:0xf
	v_fmac_f32_dpp v233, v55, v115 row_shr:2 row_mask:0xf bank_mask:0xf
	v_fmac_f32_dpp v234, v48, v116 row_shr:2 row_mask:0xf bank_mask:0xf
	v_fmac_f32_dpp v235, v49, v117 row_shr:2 row_mask:0xf bank_mask:0xf
	v_fmac_f32_dpp v236, v50, v118 row_shr:2 row_mask:0xf bank_mask:0xf
	v_fmac_f32_dpp v237, v51, v119 row_shr:2 row_mask:0xf bank_mask:0xf
	v_fmac_f32_dpp v230, v60, v120 row_shl:15 row_mask:0xf bank_mask:0xf
	v_fmac_f32_dpp v231, v61, v121 row_shl:15 row_mask:0xf bank_mask:0xf
	v_fmac_f32_dpp v232, v62, v122 row_shl:15 row_mask:0xf bank_mask:0xf
	v_fmac_f32_dpp v233, v63, v123 row_shl:15 row_mask:0xf bank_mask:0xf
	v_fmac_f32_dpp v234, v56, v124 row_shl:15 row_mask:0xf bank_mask:0xf
	v_fmac_f32_dpp v235, v57, v125 row_shl:15 row_mask:0xf bank_mask:0xf
	v_fmac_f32_dpp v236, v58, v126 row_shl:15 row_mask:0xf bank_mask:0xf
	v_fmac_f32_dpp v237, v59, v127 row_shl:15 row_mask:0xf bank_mask:0xf
	v_fmac_f32_dpp v230, v60, v112 row_shl:14 row_mask:0xf bank_mask:0xf
	v_fmac_f32_dpp v231, v61, v113 row_shl:14 row_mask:0xf bank_mask:0xf
	v_fmac_f32_dpp v232, v62, v114 row_shl:14 row_mask:0xf bank_mask:0xf
	v_fmac_f32_dpp v233, v63, v115 row_shl:14 row_mask:0xf bank_mask:0xf
	v_fmac_f32_dpp v234, v56, v116 row_shl:14 row_mask:0xf bank_mask:0xf
	v_fmac_f32_dpp v235, v57, v117 row_shl:14 row_mask:0xf bank_mask:0xf
	v_fmac_f32_dpp v236, v58, v118 row_shl:14 row_mask:0xf bank_mask:0xf
	v_fmac_f32_dpp v237, v59, v119 row_shl:14 row_mask:0xf bank_mask:0xf
	v_pk_mul_f32 v[238:239], v[230:231], v[230:231]
	v_pk_mul_f32 v[240:241], v[232:233], v[232:233]
	v_pk_fma_f32 v[238:239], v[238:239], v[248:249], v[246:247]
	v_pk_fma_f32 v[240:241], v[240:241], v[248:249], v[246:247]
	v_pk_mul_f32 v[238:239], v[230:231], v[238:239]
	v_pk_mul_f32 v[240:241], v[232:233], v[240:241]
	v_exp_f32_e32 v238, v238
	v_exp_f32_e32 v239, v239
	v_exp_f32_e32 v240, v240
	v_exp_f32_e32 v241, v241
	v_pk_add_f32 v[238:239], v[238:239], 1.0 op_sel_hi:[1,0]
	v_pk_add_f32 v[240:241], v[240:241], 1.0 op_sel_hi:[1,0]
	v_rcp_f32_e32 v238, v238
	v_rcp_f32_e32 v239, v239
	v_rcp_f32_e32 v240, v240
	v_rcp_f32_e32 v241, v241
	v_pk_mul_f32 v[230:231], v[230:231], v[234:235]
	v_pk_mul_f32 v[232:233], v[232:233], v[236:237]
	v_pk_mul_f32 v[238:239], v[230:231], v[238:239]
	v_pk_mul_f32 v[240:241], v[232:233], v[240:241]
	v_cvt_pk_bf16_f32 v182, v238, v239
	v_cvt_pk_bf16_f32 v183, v240, v241
	s_movk_i32 s15, 0xff2
	v_cmp_gt_i32_e64 s[24:25], s15, v251
	s_add_u32 s84, s58, 0x13400
	s_addc_u32 s85, s59, 0
	s_mov_b64 exec, s[24:25]
	global_store_dwordx4 v250, v[180:183], s[84:85]
	s_mov_b64 exec, -1
	s_nop 1
	v_pk_fma_f32 v[230:231], v[140:141], v[214:215], v[222:223]
	v_pk_fma_f32 v[234:235], v[136:137], v[218:219], v[226:227]
	v_pk_fma_f32 v[232:233], v[142:143], v[216:217], v[224:225]
	v_pk_fma_f32 v[236:237], v[138:139], v[220:221], v[228:229]
	v_fmac_f32_dpp v230, v140, v206 row_shr:1 row_mask:0xf bank_mask:0xf
	v_fmac_f32_dpp v231, v141, v207 row_shr:1 row_mask:0xf bank_mask:0xf
	v_fmac_f32_dpp v232, v142, v208 row_shr:1 row_mask:0xf bank_mask:0xf
	v_fmac_f32_dpp v233, v143, v209 row_shr:1 row_mask:0xf bank_mask:0xf
	v_fmac_f32_dpp v234, v136, v210 row_shr:1 row_mask:0xf bank_mask:0xf
	v_fmac_f32_dpp v235, v137, v211 row_shr:1 row_mask:0xf bank_mask:0xf
	v_fmac_f32_dpp v236, v138, v212 row_shr:1 row_mask:0xf bank_mask:0xf
	v_fmac_f32_dpp v237, v139, v213 row_shr:1 row_mask:0xf bank_mask:0xf
	v_fmac_f32_dpp v230, v140, v198 row_shr:2 row_mask:0xf bank_mask:0xf
	v_fmac_f32_dpp v231, v141, v199 row_shr:2 row_mask:0xf bank_mask:0xf
	v_fmac_f32_dpp v232, v142, v200 row_shr:2 row_mask:0xf bank_mask:0xf
	v_fmac_f32_dpp v233, v143, v201 row_shr:2 row_mask:0xf bank_mask:0xf
	v_fmac_f32_dpp v234, v136, v202 row_shr:2 row_mask:0xf bank_mask:0xf
	v_fmac_f32_dpp v235, v137, v203 row_shr:2 row_mask:0xf bank_mask:0xf
	v_fmac_f32_dpp v236, v138, v204 row_shr:2 row_mask:0xf bank_mask:0xf
	v_fmac_f32_dpp v237, v139, v205 row_shr:2 row_mask:0xf bank_mask:0xf
	v_fmac_f32_dpp v230, v148, v206 row_shl:15 row_mask:0xf bank_mask:0xf
	v_fmac_f32_dpp v231, v149, v207 row_shl:15 row_mask:0xf bank_mask:0xf
	v_fmac_f32_dpp v232, v150, v208 row_shl:15 row_mask:0xf bank_mask:0xf
	v_fmac_f32_dpp v233, v151, v209 row_shl:15 row_mask:0xf bank_mask:0xf
	v_fmac_f32_dpp v234, v144, v210 row_shl:15 row_mask:0xf bank_mask:0xf
	v_fmac_f32_dpp v235, v145, v211 row_shl:15 row_mask:0xf bank_mask:0xf
	v_fmac_f32_dpp v236, v146, v212 row_shl:15 row_mask:0xf bank_mask:0xf
	v_fmac_f32_dpp v237, v147, v213 row_shl:15 row_mask:0xf bank_mask:0xf
	v_fmac_f32_dpp v230, v148, v198 row_shl:14 row_mask:0xf bank_mask:0xf
	v_fmac_f32_dpp v231, v149, v199 row_shl:14 row_mask:0xf bank_mask:0xf
	v_fmac_f32_dpp v232, v150, v200 row_shl:14 row_mask:0xf bank_mask:0xf
	v_fmac_f32_dpp v233, v151, v201 row_shl:14 row_mask:0xf bank_mask:0xf
	v_fmac_f32_dpp v234, v144, v202 row_shl:14 row_mask:0xf bank_mask:0xf
	v_fmac_f32_dpp v235, v145, v203 row_shl:14 row_mask:0xf bank_mask:0xf
	v_fmac_f32_dpp v236, v146, v204 row_shl:14 row_mask:0xf bank_mask:0xf
	v_fmac_f32_dpp v237, v147, v205 row_shl:14 row_mask:0xf bank_mask:0xf
	v_pk_mul_f32 v[238:239], v[230:231], v[230:231]
	v_pk_mul_f32 v[240:241], v[232:233], v[232:233]
	v_pk_fma_f32 v[238:239], v[238:239], v[248:249], v[246:247]
	v_pk_fma_f32 v[240:241], v[240:241], v[248:249], v[246:247]
	v_pk_mul_f32 v[238:239], v[230:231], v[238:239]
	v_pk_mul_f32 v[240:241], v[232:233], v[240:241]
	v_exp_f32_e32 v238, v238
	v_exp_f32_e32 v239, v239
	v_exp_f32_e32 v240, v240
	v_exp_f32_e32 v241, v241
	v_pk_add_f32 v[238:239], v[238:239], 1.0 op_sel_hi:[1,0]
	v_pk_add_f32 v[240:241], v[240:241], 1.0 op_sel_hi:[1,0]
	v_rcp_f32_e32 v238, v238
	v_rcp_f32_e32 v239, v239
	v_rcp_f32_e32 v240, v240
	v_rcp_f32_e32 v241, v241
	v_pk_mul_f32 v[230:231], v[230:231], v[234:235]
	v_pk_mul_f32 v[232:233], v[232:233], v[236:237]
	v_pk_mul_f32 v[238:239], v[230:231], v[238:239]
	v_pk_mul_f32 v[240:241], v[232:233], v[240:241]
	v_cvt_pk_bf16_f32 v176, v238, v239
	v_cvt_pk_bf16_f32 v177, v240, v241
	v_pk_fma_f32 v[230:231], v[44:45], v[128:129], v[100:101]
	v_pk_fma_f32 v[234:235], v[40:41], v[132:133], v[104:105]
	v_pk_fma_f32 v[232:233], v[46:47], v[130:131], v[102:103]
	v_pk_fma_f32 v[236:237], v[42:43], v[134:135], v[106:107]
	v_fmac_f32_dpp v230, v44, v120 row_shr:1 row_mask:0xf bank_mask:0xf
	v_fmac_f32_dpp v231, v45, v121 row_shr:1 row_mask:0xf bank_mask:0xf
	v_fmac_f32_dpp v232, v46, v122 row_shr:1 row_mask:0xf bank_mask:0xf
	v_fmac_f32_dpp v233, v47, v123 row_shr:1 row_mask:0xf bank_mask:0xf
	v_fmac_f32_dpp v234, v40, v124 row_shr:1 row_mask:0xf bank_mask:0xf
	v_fmac_f32_dpp v235, v41, v125 row_shr:1 row_mask:0xf bank_mask:0xf
	v_fmac_f32_dpp v236, v42, v126 row_shr:1 row_mask:0xf bank_mask:0xf
	v_fmac_f32_dpp v237, v43, v127 row_shr:1 row_mask:0xf bank_mask:0xf
	v_fmac_f32_dpp v230, v44, v112 row_shr:2 row_mask:0xf bank_mask:0xf
	v_fmac_f32_dpp v231, v45, v113 row_shr:2 row_mask:0xf bank_mask:0xf
	v_fmac_f32_dpp v232, v46, v114 row_shr:2 row_mask:0xf bank_mask:0xf
	v_fmac_f32_dpp v233, v47, v115 row_shr:2 row_mask:0xf bank_mask:0xf
	v_fmac_f32_dpp v234, v40, v116 row_shr:2 row_mask:0xf bank_mask:0xf
	v_fmac_f32_dpp v235, v41, v117 row_shr:2 row_mask:0xf bank_mask:0xf
	v_fmac_f32_dpp v236, v42, v118 row_shr:2 row_mask:0xf bank_mask:0xf
	v_fmac_f32_dpp v237, v43, v119 row_shr:2 row_mask:0xf bank_mask:0xf
	v_fmac_f32_dpp v230, v52, v120 row_shl:15 row_mask:0xf bank_mask:0xf
	v_fmac_f32_dpp v231, v53, v121 row_shl:15 row_mask:0xf bank_mask:0xf
	v_fmac_f32_dpp v232, v54, v122 row_shl:15 row_mask:0xf bank_mask:0xf
	v_fmac_f32_dpp v233, v55, v123 row_shl:15 row_mask:0xf bank_mask:0xf
	v_fmac_f32_dpp v234, v48, v124 row_shl:15 row_mask:0xf bank_mask:0xf
	v_fmac_f32_dpp v235, v49, v125 row_shl:15 row_mask:0xf bank_mask:0xf
	v_fmac_f32_dpp v236, v50, v126 row_shl:15 row_mask:0xf bank_mask:0xf
	v_fmac_f32_dpp v237, v51, v127 row_shl:15 row_mask:0xf bank_mask:0xf
	v_fmac_f32_dpp v230, v52, v112 row_shl:14 row_mask:0xf bank_mask:0xf
	v_fmac_f32_dpp v231, v53, v113 row_shl:14 row_mask:0xf bank_mask:0xf
	v_fmac_f32_dpp v232, v54, v114 row_shl:14 row_mask:0xf bank_mask:0xf
	v_fmac_f32_dpp v233, v55, v115 row_shl:14 row_mask:0xf bank_mask:0xf
	v_fmac_f32_dpp v234, v48, v116 row_shl:14 row_mask:0xf bank_mask:0xf
	v_fmac_f32_dpp v235, v49, v117 row_shl:14 row_mask:0xf bank_mask:0xf
	v_fmac_f32_dpp v236, v50, v118 row_shl:14 row_mask:0xf bank_mask:0xf
	v_fmac_f32_dpp v237, v51, v119 row_shl:14 row_mask:0xf bank_mask:0xf
	v_pk_mul_f32 v[238:239], v[230:231], v[230:231]
	v_pk_mul_f32 v[240:241], v[232:233], v[232:233]
	v_pk_fma_f32 v[238:239], v[238:239], v[248:249], v[246:247]
	v_pk_fma_f32 v[240:241], v[240:241], v[248:249], v[246:247]
	v_pk_mul_f32 v[238:239], v[230:231], v[238:239]
	v_pk_mul_f32 v[240:241], v[232:233], v[240:241]
	v_exp_f32_e32 v238, v238
	v_exp_f32_e32 v239, v239
	v_exp_f32_e32 v240, v240
	v_exp_f32_e32 v241, v241
	v_pk_add_f32 v[238:239], v[238:239], 1.0 op_sel_hi:[1,0]
	v_pk_add_f32 v[240:241], v[240:241], 1.0 op_sel_hi:[1,0]
	v_rcp_f32_e32 v238, v238
	v_rcp_f32_e32 v239, v239
	v_rcp_f32_e32 v240, v240
	v_rcp_f32_e32 v241, v241
	v_pk_mul_f32 v[230:231], v[230:231], v[234:235]
	v_pk_mul_f32 v[232:233], v[232:233], v[236:237]
	v_pk_mul_f32 v[238:239], v[230:231], v[238:239]
	v_pk_mul_f32 v[240:241], v[232:233], v[240:241]
	v_cvt_pk_bf16_f32 v178, v238, v239
	v_cvt_pk_bf16_f32 v179, v240, v241
	s_movk_i32 s15, 0xfe2
	v_cmp_gt_i32_e64 s[24:25], s15, v251
	s_add_u32 s84, s58, 0x29400
	s_addc_u32 s85, s59, 0
	s_mov_b64 exec, s[24:25]
	global_store_dwordx4 v250, v[176:179], s[84:85]
	s_mov_b64 exec, -1
	s_nop 1
	v_pk_fma_f32 v[230:231], v[108:109], v[214:215], v[222:223]
	v_pk_fma_f32 v[234:235], v[96:97], v[218:219], v[226:227]
	v_pk_fma_f32 v[232:233], v[110:111], v[216:217], v[224:225]
	v_pk_fma_f32 v[236:237], v[98:99], v[220:221], v[228:229]
	v_fmac_f32_dpp v230, v108, v206 row_shr:1 row_mask:0xf bank_mask:0xf
	v_fmac_f32_dpp v231, v109, v207 row_shr:1 row_mask:0xf bank_mask:0xf
	v_fmac_f32_dpp v232, v110, v208 row_shr:1 row_mask:0xf bank_mask:0xf
	v_fmac_f32_dpp v233, v111, v209 row_shr:1 row_mask:0xf bank_mask:0xf
	v_fmac_f32_dpp v234, v96, v210 row_shr:1 row_mask:0xf bank_mask:0xf
	v_fmac_f32_dpp v235, v97, v211 row_shr:1 row_mask:0xf bank_mask:0xf
	v_fmac_f32_dpp v236, v98, v212 row_shr:1 row_mask:0xf bank_mask:0xf
	v_fmac_f32_dpp v237, v99, v213 row_shr:1 row_mask:0xf bank_mask:0xf
	v_fmac_f32_dpp v230, v108, v198 row_shr:2 row_mask:0xf bank_mask:0xf
	v_fmac_f32_dpp v231, v109, v199 row_shr:2 row_mask:0xf bank_mask:0xf
	v_fmac_f32_dpp v232, v110, v200 row_shr:2 row_mask:0xf bank_mask:0xf
	v_fmac_f32_dpp v233, v111, v201 row_shr:2 row_mask:0xf bank_mask:0xf
	v_fmac_f32_dpp v234, v96, v202 row_shr:2 row_mask:0xf bank_mask:0xf
	v_fmac_f32_dpp v235, v97, v203 row_shr:2 row_mask:0xf bank_mask:0xf
	v_fmac_f32_dpp v236, v98, v204 row_shr:2 row_mask:0xf bank_mask:0xf
	v_fmac_f32_dpp v237, v99, v205 row_shr:2 row_mask:0xf bank_mask:0xf
	v_fmac_f32_dpp v230, v140, v206 row_shl:15 row_mask:0xf bank_mask:0xf
	v_fmac_f32_dpp v231, v141, v207 row_shl:15 row_mask:0xf bank_mask:0xf
	v_fmac_f32_dpp v232, v142, v208 row_shl:15 row_mask:0xf bank_mask:0xf
	v_fmac_f32_dpp v233, v143, v209 row_shl:15 row_mask:0xf bank_mask:0xf
	v_fmac_f32_dpp v234, v136, v210 row_shl:15 row_mask:0xf bank_mask:0xf
	v_fmac_f32_dpp v235, v137, v211 row_shl:15 row_mask:0xf bank_mask:0xf
	v_fmac_f32_dpp v236, v138, v212 row_shl:15 row_mask:0xf bank_mask:0xf
	v_fmac_f32_dpp v237, v139, v213 row_shl:15 row_mask:0xf bank_mask:0xf
	v_fmac_f32_dpp v230, v140, v198 row_shl:14 row_mask:0xf bank_mask:0xf
	v_fmac_f32_dpp v231, v141, v199 row_shl:14 row_mask:0xf bank_mask:0xf
	v_fmac_f32_dpp v232, v142, v200 row_shl:14 row_mask:0xf bank_mask:0xf
	v_fmac_f32_dpp v233, v143, v201 row_shl:14 row_mask:0xf bank_mask:0xf
	v_fmac_f32_dpp v234, v136, v202 row_shl:14 row_mask:0xf bank_mask:0xf
	v_fmac_f32_dpp v235, v137, v203 row_shl:14 row_mask:0xf bank_mask:0xf
	v_fmac_f32_dpp v236, v138, v204 row_shl:14 row_mask:0xf bank_mask:0xf
	v_fmac_f32_dpp v237, v139, v205 row_shl:14 row_mask:0xf bank_mask:0xf
	v_pk_mul_f32 v[238:239], v[230:231], v[230:231]
	v_pk_mul_f32 v[240:241], v[232:233], v[232:233]
	v_pk_fma_f32 v[238:239], v[238:239], v[248:249], v[246:247]
	v_pk_fma_f32 v[240:241], v[240:241], v[248:249], v[246:247]
	v_pk_mul_f32 v[238:239], v[230:231], v[238:239]
	v_pk_mul_f32 v[240:241], v[232:233], v[240:241]
	v_exp_f32_e32 v238, v238
	v_exp_f32_e32 v239, v239
	v_exp_f32_e32 v240, v240
	v_exp_f32_e32 v241, v241
	v_pk_add_f32 v[238:239], v[238:239], 1.0 op_sel_hi:[1,0]
	v_pk_add_f32 v[240:241], v[240:241], 1.0 op_sel_hi:[1,0]
	v_rcp_f32_e32 v238, v238
	v_rcp_f32_e32 v239, v239
	v_rcp_f32_e32 v240, v240
	v_rcp_f32_e32 v241, v241
	v_pk_mul_f32 v[230:231], v[230:231], v[234:235]
	v_pk_mul_f32 v[232:233], v[232:233], v[236:237]
	v_pk_mul_f32 v[238:239], v[230:231], v[238:239]
	v_pk_mul_f32 v[240:241], v[232:233], v[240:241]
	v_cvt_pk_bf16_f32 v180, v238, v239
	v_cvt_pk_bf16_f32 v181, v240, v241
	v_pk_fma_f32 v[230:231], v[36:37], v[128:129], v[100:101]
	v_pk_fma_f32 v[234:235], v[32:33], v[132:133], v[104:105]
	v_pk_fma_f32 v[232:233], v[38:39], v[130:131], v[102:103]
	v_pk_fma_f32 v[236:237], v[34:35], v[134:135], v[106:107]
	v_fmac_f32_dpp v230, v36, v120 row_shr:1 row_mask:0xf bank_mask:0xf
	v_fmac_f32_dpp v231, v37, v121 row_shr:1 row_mask:0xf bank_mask:0xf
	v_fmac_f32_dpp v232, v38, v122 row_shr:1 row_mask:0xf bank_mask:0xf
	v_fmac_f32_dpp v233, v39, v123 row_shr:1 row_mask:0xf bank_mask:0xf
	v_fmac_f32_dpp v234, v32, v124 row_shr:1 row_mask:0xf bank_mask:0xf
	v_fmac_f32_dpp v235, v33, v125 row_shr:1 row_mask:0xf bank_mask:0xf
	v_fmac_f32_dpp v236, v34, v126 row_shr:1 row_mask:0xf bank_mask:0xf
	v_fmac_f32_dpp v237, v35, v127 row_shr:1 row_mask:0xf bank_mask:0xf
	v_fmac_f32_dpp v230, v36, v112 row_shr:2 row_mask:0xf bank_mask:0xf
	v_fmac_f32_dpp v231, v37, v113 row_shr:2 row_mask:0xf bank_mask:0xf
	v_fmac_f32_dpp v232, v38, v114 row_shr:2 row_mask:0xf bank_mask:0xf
	v_fmac_f32_dpp v233, v39, v115 row_shr:2 row_mask:0xf bank_mask:0xf
	v_fmac_f32_dpp v234, v32, v116 row_shr:2 row_mask:0xf bank_mask:0xf
	v_fmac_f32_dpp v235, v33, v117 row_shr:2 row_mask:0xf bank_mask:0xf
	v_fmac_f32_dpp v236, v34, v118 row_shr:2 row_mask:0xf bank_mask:0xf
	v_fmac_f32_dpp v237, v35, v119 row_shr:2 row_mask:0xf bank_mask:0xf
	v_fmac_f32_dpp v230, v44, v120 row_shl:15 row_mask:0xf bank_mask:0xf
	v_fmac_f32_dpp v231, v45, v121 row_shl:15 row_mask:0xf bank_mask:0xf
	v_fmac_f32_dpp v232, v46, v122 row_shl:15 row_mask:0xf bank_mask:0xf
	v_fmac_f32_dpp v233, v47, v123 row_shl:15 row_mask:0xf bank_mask:0xf
	v_fmac_f32_dpp v234, v40, v124 row_shl:15 row_mask:0xf bank_mask:0xf
	v_fmac_f32_dpp v235, v41, v125 row_shl:15 row_mask:0xf bank_mask:0xf
	v_fmac_f32_dpp v236, v42, v126 row_shl:15 row_mask:0xf bank_mask:0xf
	v_fmac_f32_dpp v237, v43, v127 row_shl:15 row_mask:0xf bank_mask:0xf
	v_fmac_f32_dpp v230, v44, v112 row_shl:14 row_mask:0xf bank_mask:0xf
	v_fmac_f32_dpp v231, v45, v113 row_shl:14 row_mask:0xf bank_mask:0xf
	v_fmac_f32_dpp v232, v46, v114 row_shl:14 row_mask:0xf bank_mask:0xf
	v_fmac_f32_dpp v233, v47, v115 row_shl:14 row_mask:0xf bank_mask:0xf
	v_fmac_f32_dpp v234, v40, v116 row_shl:14 row_mask:0xf bank_mask:0xf
	v_fmac_f32_dpp v235, v41, v117 row_shl:14 row_mask:0xf bank_mask:0xf
	v_fmac_f32_dpp v236, v42, v118 row_shl:14 row_mask:0xf bank_mask:0xf
	v_fmac_f32_dpp v237, v43, v119 row_shl:14 row_mask:0xf bank_mask:0xf
	v_pk_mul_f32 v[238:239], v[230:231], v[230:231]
	v_pk_mul_f32 v[240:241], v[232:233], v[232:233]
	v_pk_fma_f32 v[238:239], v[238:239], v[248:249], v[246:247]
	v_pk_fma_f32 v[240:241], v[240:241], v[248:249], v[246:247]
	v_pk_mul_f32 v[238:239], v[230:231], v[238:239]
	v_pk_mul_f32 v[240:241], v[232:233], v[240:241]
	v_exp_f32_e32 v238, v238
	v_exp_f32_e32 v239, v239
	v_exp_f32_e32 v240, v240
	v_exp_f32_e32 v241, v241
	v_pk_add_f32 v[238:239], v[238:239], 1.0 op_sel_hi:[1,0]
	v_pk_add_f32 v[240:241], v[240:241], 1.0 op_sel_hi:[1,0]
	v_rcp_f32_e32 v238, v238
	v_rcp_f32_e32 v239, v239
	v_rcp_f32_e32 v240, v240
	v_rcp_f32_e32 v241, v241
	v_pk_mul_f32 v[230:231], v[230:231], v[234:235]
	v_pk_mul_f32 v[232:233], v[232:233], v[236:237]
	v_pk_mul_f32 v[238:239], v[230:231], v[238:239]
	v_pk_mul_f32 v[240:241], v[232:233], v[240:241]
	v_cvt_pk_bf16_f32 v182, v238, v239
	v_cvt_pk_bf16_f32 v183, v240, v241
	s_movk_i32 s15, 0xfd2
	v_cmp_gt_i32_e64 s[24:25], s15, v251
	s_add_u32 s84, s58, 0x3f400
	s_addc_u32 s85, s59, 0
	s_mov_b64 exec, s[24:25]
	global_store_dwordx4 v250, v[180:183], s[84:85]
	s_mov_b64 exec, -1
	s_nop 1
	v_pk_fma_f32 v[230:231], v[92:93], v[214:215], v[222:223]
	v_pk_fma_f32 v[234:235], v[88:89], v[218:219], v[226:227]
	v_pk_fma_f32 v[232:233], v[94:95], v[216:217], v[224:225]
	v_pk_fma_f32 v[236:237], v[90:91], v[220:221], v[228:229]
	v_fmac_f32_dpp v230, v92, v206 row_shr:1 row_mask:0xf bank_mask:0xf
	v_fmac_f32_dpp v231, v93, v207 row_shr:1 row_mask:0xf bank_mask:0xf
	v_fmac_f32_dpp v232, v94, v208 row_shr:1 row_mask:0xf bank_mask:0xf
	v_fmac_f32_dpp v233, v95, v209 row_shr:1 row_mask:0xf bank_mask:0xf
	v_fmac_f32_dpp v234, v88, v210 row_shr:1 row_mask:0xf bank_mask:0xf
	v_fmac_f32_dpp v235, v89, v211 row_shr:1 row_mask:0xf bank_mask:0xf
	v_fmac_f32_dpp v236, v90, v212 row_shr:1 row_mask:0xf bank_mask:0xf
	v_fmac_f32_dpp v237, v91, v213 row_shr:1 row_mask:0xf bank_mask:0xf
	v_fmac_f32_dpp v230, v92, v198 row_shr:2 row_mask:0xf bank_mask:0xf
	v_fmac_f32_dpp v231, v93, v199 row_shr:2 row_mask:0xf bank_mask:0xf
	v_fmac_f32_dpp v232, v94, v200 row_shr:2 row_mask:0xf bank_mask:0xf
	v_fmac_f32_dpp v233, v95, v201 row_shr:2 row_mask:0xf bank_mask:0xf
	v_fmac_f32_dpp v234, v88, v202 row_shr:2 row_mask:0xf bank_mask:0xf
	v_fmac_f32_dpp v235, v89, v203 row_shr:2 row_mask:0xf bank_mask:0xf
	v_fmac_f32_dpp v236, v90, v204 row_shr:2 row_mask:0xf bank_mask:0xf
	v_fmac_f32_dpp v237, v91, v205 row_shr:2 row_mask:0xf bank_mask:0xf
	v_pk_mul_f32 v[238:239], v[230:231], v[230:231]
	v_pk_mul_f32 v[240:241], v[232:233], v[232:233]
	v_pk_fma_f32 v[238:239], v[238:239], v[248:249], v[246:247]
	v_pk_fma_f32 v[240:241], v[240:241], v[248:249], v[246:247]
	v_pk_mul_f32 v[238:239], v[230:231], v[238:239]
	v_pk_mul_f32 v[240:241], v[232:233], v[240:241]
	v_exp_f32_e32 v238, v238
	v_exp_f32_e32 v239, v239
	v_exp_f32_e32 v240, v240
	v_exp_f32_e32 v241, v241
	v_pk_add_f32 v[238:239], v[238:239], 1.0 op_sel_hi:[1,0]
	v_pk_add_f32 v[240:241], v[240:241], 1.0 op_sel_hi:[1,0]
	v_rcp_f32_e32 v238, v238
	v_rcp_f32_e32 v239, v239
	v_rcp_f32_e32 v240, v240
	v_rcp_f32_e32 v241, v241
	v_pk_mul_f32 v[230:231], v[230:231], v[234:235]
	v_pk_mul_f32 v[232:233], v[232:233], v[236:237]
	v_pk_mul_f32 v[238:239], v[230:231], v[238:239]
	v_pk_mul_f32 v[240:241], v[232:233], v[240:241]
	v_cvt_pk_bf16_f32 v176, v238, v239
	v_cvt_pk_bf16_f32 v177, v240, v241
	v_pk_fma_f32 v[230:231], v[28:29], v[128:129], v[100:101]
	v_pk_fma_f32 v[234:235], v[24:25], v[132:133], v[104:105]
	v_pk_fma_f32 v[232:233], v[30:31], v[130:131], v[102:103]
	v_pk_fma_f32 v[236:237], v[26:27], v[134:135], v[106:107]
	v_fmac_f32_dpp v230, v28, v120 row_shr:1 row_mask:0xf bank_mask:0xf
	v_fmac_f32_dpp v231, v29, v121 row_shr:1 row_mask:0xf bank_mask:0xf
	v_fmac_f32_dpp v232, v30, v122 row_shr:1 row_mask:0xf bank_mask:0xf
	v_fmac_f32_dpp v233, v31, v123 row_shr:1 row_mask:0xf bank_mask:0xf
	v_fmac_f32_dpp v234, v24, v124 row_shr:1 row_mask:0xf bank_mask:0xf
	v_fmac_f32_dpp v235, v25, v125 row_shr:1 row_mask:0xf bank_mask:0xf
	v_fmac_f32_dpp v236, v26, v126 row_shr:1 row_mask:0xf bank_mask:0xf
	v_fmac_f32_dpp v237, v27, v127 row_shr:1 row_mask:0xf bank_mask:0xf
	v_fmac_f32_dpp v230, v28, v112 row_shr:2 row_mask:0xf bank_mask:0xf
	v_fmac_f32_dpp v231, v29, v113 row_shr:2 row_mask:0xf bank_mask:0xf
	v_fmac_f32_dpp v232, v30, v114 row_shr:2 row_mask:0xf bank_mask:0xf
	v_fmac_f32_dpp v233, v31, v115 row_shr:2 row_mask:0xf bank_mask:0xf
	v_fmac_f32_dpp v234, v24, v116 row_shr:2 row_mask:0xf bank_mask:0xf
	v_fmac_f32_dpp v235, v25, v117 row_shr:2 row_mask:0xf bank_mask:0xf
	v_fmac_f32_dpp v236, v26, v118 row_shr:2 row_mask:0xf bank_mask:0xf
	v_fmac_f32_dpp v237, v27, v119 row_shr:2 row_mask:0xf bank_mask:0xf
	v_pk_mul_f32 v[238:239], v[230:231], v[230:231]
	v_pk_mul_f32 v[240:241], v[232:233], v[232:233]
	v_pk_fma_f32 v[238:239], v[238:239], v[248:249], v[246:247]
	v_pk_fma_f32 v[240:241], v[240:241], v[248:249], v[246:247]
	v_pk_mul_f32 v[238:239], v[230:231], v[238:239]
	v_pk_mul_f32 v[240:241], v[232:233], v[240:241]
	v_exp_f32_e32 v238, v238
	v_exp_f32_e32 v239, v239
	v_exp_f32_e32 v240, v240
	v_exp_f32_e32 v241, v241
	v_pk_add_f32 v[238:239], v[238:239], 1.0 op_sel_hi:[1,0]
	v_pk_add_f32 v[240:241], v[240:241], 1.0 op_sel_hi:[1,0]
	v_rcp_f32_e32 v238, v238
	v_rcp_f32_e32 v239, v239
	v_rcp_f32_e32 v240, v240
	v_rcp_f32_e32 v241, v241
	v_pk_mul_f32 v[230:231], v[230:231], v[234:235]
	v_pk_mul_f32 v[232:233], v[232:233], v[236:237]
	v_pk_mul_f32 v[238:239], v[230:231], v[238:239]
	v_pk_mul_f32 v[240:241], v[232:233], v[240:241]
	v_cvt_pk_bf16_f32 v178, v238, v239
	v_cvt_pk_bf16_f32 v179, v240, v241
	s_movk_i32 s15, 0xf86
	v_cmp_gt_i32_e64 s[24:25], s15, v251
	s_add_u32 s84, s58, 0xa7c00
	s_addc_u32 s85, s59, 0
	s_and_b64 s[24:25], s[24:25], s[4:5]
	s_mov_b64 exec, s[24:25]
	global_store_dwordx4 v250, v[176:179], s[84:85]
	s_mov_b64 exec, -1
	s_nop 1
	v_pk_fma_f32 v[230:231], v[84:85], v[214:215], v[222:223]
	v_pk_fma_f32 v[234:235], v[80:81], v[218:219], v[226:227]
	v_pk_fma_f32 v[232:233], v[86:87], v[216:217], v[224:225]
	v_pk_fma_f32 v[236:237], v[82:83], v[220:221], v[228:229]
	v_fmac_f32_dpp v230, v84, v206 row_shr:1 row_mask:0xf bank_mask:0xf
	v_fmac_f32_dpp v231, v85, v207 row_shr:1 row_mask:0xf bank_mask:0xf
	v_fmac_f32_dpp v232, v86, v208 row_shr:1 row_mask:0xf bank_mask:0xf
	v_fmac_f32_dpp v233, v87, v209 row_shr:1 row_mask:0xf bank_mask:0xf
	v_fmac_f32_dpp v234, v80, v210 row_shr:1 row_mask:0xf bank_mask:0xf
	v_fmac_f32_dpp v235, v81, v211 row_shr:1 row_mask:0xf bank_mask:0xf
	v_fmac_f32_dpp v236, v82, v212 row_shr:1 row_mask:0xf bank_mask:0xf
	v_fmac_f32_dpp v237, v83, v213 row_shr:1 row_mask:0xf bank_mask:0xf
	v_fmac_f32_dpp v230, v84, v198 row_shr:2 row_mask:0xf bank_mask:0xf
	v_fmac_f32_dpp v231, v85, v199 row_shr:2 row_mask:0xf bank_mask:0xf
	v_fmac_f32_dpp v232, v86, v200 row_shr:2 row_mask:0xf bank_mask:0xf
	v_fmac_f32_dpp v233, v87, v201 row_shr:2 row_mask:0xf bank_mask:0xf
	v_fmac_f32_dpp v234, v80, v202 row_shr:2 row_mask:0xf bank_mask:0xf
	v_fmac_f32_dpp v235, v81, v203 row_shr:2 row_mask:0xf bank_mask:0xf
	v_fmac_f32_dpp v236, v82, v204 row_shr:2 row_mask:0xf bank_mask:0xf
	v_fmac_f32_dpp v237, v83, v205 row_shr:2 row_mask:0xf bank_mask:0xf
	v_fmac_f32_dpp v230, v92, v206 row_shl:15 row_mask:0xf bank_mask:0xf
	v_fmac_f32_dpp v231, v93, v207 row_shl:15 row_mask:0xf bank_mask:0xf
	v_fmac_f32_dpp v232, v94, v208 row_shl:15 row_mask:0xf bank_mask:0xf
	v_fmac_f32_dpp v233, v95, v209 row_shl:15 row_mask:0xf bank_mask:0xf
	v_fmac_f32_dpp v234, v88, v210 row_shl:15 row_mask:0xf bank_mask:0xf
	v_fmac_f32_dpp v235, v89, v211 row_shl:15 row_mask:0xf bank_mask:0xf
	v_fmac_f32_dpp v236, v90, v212 row_shl:15 row_mask:0xf bank_mask:0xf
	v_fmac_f32_dpp v237, v91, v213 row_shl:15 row_mask:0xf bank_mask:0xf
	v_fmac_f32_dpp v230, v92, v198 row_shl:14 row_mask:0xf bank_mask:0xf
	v_fmac_f32_dpp v231, v93, v199 row_shl:14 row_mask:0xf bank_mask:0xf
	v_fmac_f32_dpp v232, v94, v200 row_shl:14 row_mask:0xf bank_mask:0xf
	v_fmac_f32_dpp v233, v95, v201 row_shl:14 row_mask:0xf bank_mask:0xf
	v_fmac_f32_dpp v234, v88, v202 row_shl:14 row_mask:0xf bank_mask:0xf
	v_fmac_f32_dpp v235, v89, v203 row_shl:14 row_mask:0xf bank_mask:0xf
	v_fmac_f32_dpp v236, v90, v204 row_shl:14 row_mask:0xf bank_mask:0xf
	v_fmac_f32_dpp v237, v91, v205 row_shl:14 row_mask:0xf bank_mask:0xf
	v_pk_mul_f32 v[238:239], v[230:231], v[230:231]
	v_pk_mul_f32 v[240:241], v[232:233], v[232:233]
	v_pk_fma_f32 v[238:239], v[238:239], v[248:249], v[246:247]
	v_pk_fma_f32 v[240:241], v[240:241], v[248:249], v[246:247]
	v_pk_mul_f32 v[238:239], v[230:231], v[238:239]
	v_pk_mul_f32 v[240:241], v[232:233], v[240:241]
	v_exp_f32_e32 v238, v238
	v_exp_f32_e32 v239, v239
	v_exp_f32_e32 v240, v240
	v_exp_f32_e32 v241, v241
	v_pk_add_f32 v[238:239], v[238:239], 1.0 op_sel_hi:[1,0]
	v_pk_add_f32 v[240:241], v[240:241], 1.0 op_sel_hi:[1,0]
	v_rcp_f32_e32 v238, v238
	v_rcp_f32_e32 v239, v239
	v_rcp_f32_e32 v240, v240
	v_rcp_f32_e32 v241, v241
	v_pk_mul_f32 v[230:231], v[230:231], v[234:235]
	v_pk_mul_f32 v[232:233], v[232:233], v[236:237]
	v_pk_mul_f32 v[238:239], v[230:231], v[238:239]
	v_pk_mul_f32 v[240:241], v[232:233], v[240:241]
	v_cvt_pk_bf16_f32 v180, v238, v239
	v_cvt_pk_bf16_f32 v181, v240, v241
	v_pk_fma_f32 v[230:231], v[20:21], v[128:129], v[100:101]
	v_pk_fma_f32 v[234:235], v[16:17], v[132:133], v[104:105]
	v_pk_fma_f32 v[232:233], v[22:23], v[130:131], v[102:103]
	v_pk_fma_f32 v[236:237], v[18:19], v[134:135], v[106:107]
	v_fmac_f32_dpp v230, v20, v120 row_shr:1 row_mask:0xf bank_mask:0xf
	v_fmac_f32_dpp v231, v21, v121 row_shr:1 row_mask:0xf bank_mask:0xf
	v_fmac_f32_dpp v232, v22, v122 row_shr:1 row_mask:0xf bank_mask:0xf
	v_fmac_f32_dpp v233, v23, v123 row_shr:1 row_mask:0xf bank_mask:0xf
	v_fmac_f32_dpp v234, v16, v124 row_shr:1 row_mask:0xf bank_mask:0xf
	v_fmac_f32_dpp v235, v17, v125 row_shr:1 row_mask:0xf bank_mask:0xf
	v_fmac_f32_dpp v236, v18, v126 row_shr:1 row_mask:0xf bank_mask:0xf
	v_fmac_f32_dpp v237, v19, v127 row_shr:1 row_mask:0xf bank_mask:0xf
	v_fmac_f32_dpp v230, v20, v112 row_shr:2 row_mask:0xf bank_mask:0xf
	v_fmac_f32_dpp v231, v21, v113 row_shr:2 row_mask:0xf bank_mask:0xf
	v_fmac_f32_dpp v232, v22, v114 row_shr:2 row_mask:0xf bank_mask:0xf
	v_fmac_f32_dpp v233, v23, v115 row_shr:2 row_mask:0xf bank_mask:0xf
	v_fmac_f32_dpp v234, v16, v116 row_shr:2 row_mask:0xf bank_mask:0xf
	v_fmac_f32_dpp v235, v17, v117 row_shr:2 row_mask:0xf bank_mask:0xf
	v_fmac_f32_dpp v236, v18, v118 row_shr:2 row_mask:0xf bank_mask:0xf
	v_fmac_f32_dpp v237, v19, v119 row_shr:2 row_mask:0xf bank_mask:0xf
	v_fmac_f32_dpp v230, v28, v120 row_shl:15 row_mask:0xf bank_mask:0xf
	v_fmac_f32_dpp v231, v29, v121 row_shl:15 row_mask:0xf bank_mask:0xf
	v_fmac_f32_dpp v232, v30, v122 row_shl:15 row_mask:0xf bank_mask:0xf
	v_fmac_f32_dpp v233, v31, v123 row_shl:15 row_mask:0xf bank_mask:0xf
	v_fmac_f32_dpp v234, v24, v124 row_shl:15 row_mask:0xf bank_mask:0xf
	v_fmac_f32_dpp v235, v25, v125 row_shl:15 row_mask:0xf bank_mask:0xf
	v_fmac_f32_dpp v236, v26, v126 row_shl:15 row_mask:0xf bank_mask:0xf
	v_fmac_f32_dpp v237, v27, v127 row_shl:15 row_mask:0xf bank_mask:0xf
	v_fmac_f32_dpp v230, v28, v112 row_shl:14 row_mask:0xf bank_mask:0xf
	v_fmac_f32_dpp v231, v29, v113 row_shl:14 row_mask:0xf bank_mask:0xf
	v_fmac_f32_dpp v232, v30, v114 row_shl:14 row_mask:0xf bank_mask:0xf
	v_fmac_f32_dpp v233, v31, v115 row_shl:14 row_mask:0xf bank_mask:0xf
	v_fmac_f32_dpp v234, v24, v116 row_shl:14 row_mask:0xf bank_mask:0xf
	v_fmac_f32_dpp v235, v25, v117 row_shl:14 row_mask:0xf bank_mask:0xf
	v_fmac_f32_dpp v236, v26, v118 row_shl:14 row_mask:0xf bank_mask:0xf
	v_fmac_f32_dpp v237, v27, v119 row_shl:14 row_mask:0xf bank_mask:0xf
	v_pk_mul_f32 v[238:239], v[230:231], v[230:231]
	v_pk_mul_f32 v[240:241], v[232:233], v[232:233]
	v_pk_fma_f32 v[238:239], v[238:239], v[248:249], v[246:247]
	v_pk_fma_f32 v[240:241], v[240:241], v[248:249], v[246:247]
	v_pk_mul_f32 v[238:239], v[230:231], v[238:239]
	v_pk_mul_f32 v[240:241], v[232:233], v[240:241]
	v_exp_f32_e32 v238, v238
	v_exp_f32_e32 v239, v239
	v_exp_f32_e32 v240, v240
	v_exp_f32_e32 v241, v241
	v_pk_add_f32 v[238:239], v[238:239], 1.0 op_sel_hi:[1,0]
	v_pk_add_f32 v[240:241], v[240:241], 1.0 op_sel_hi:[1,0]
	v_rcp_f32_e32 v238, v238
	v_rcp_f32_e32 v239, v239
	v_rcp_f32_e32 v240, v240
	v_rcp_f32_e32 v241, v241
	v_pk_mul_f32 v[230:231], v[230:231], v[234:235]
	v_pk_mul_f32 v[232:233], v[232:233], v[236:237]
	v_pk_mul_f32 v[238:239], v[230:231], v[238:239]
	v_pk_mul_f32 v[240:241], v[232:233], v[240:241]
	v_cvt_pk_bf16_f32 v182, v238, v239
	v_cvt_pk_bf16_f32 v183, v240, v241
	s_movk_i32 s15, 0xf76
	v_cmp_gt_i32_e64 s[24:25], s15, v251
	s_add_u32 s84, s58, 0xbdc00
	s_addc_u32 s85, s59, 0
	s_mov_b64 exec, s[24:25]
	global_store_dwordx4 v250, v[180:183], s[84:85]
	s_mov_b64 exec, -1
	s_nop 1
	v_pk_fma_f32 v[230:231], v[76:77], v[214:215], v[222:223]
	v_pk_fma_f32 v[234:235], v[72:73], v[218:219], v[226:227]
	v_pk_fma_f32 v[232:233], v[78:79], v[216:217], v[224:225]
	v_pk_fma_f32 v[236:237], v[74:75], v[220:221], v[228:229]
	v_fmac_f32_dpp v230, v76, v206 row_shr:1 row_mask:0xf bank_mask:0xf
	v_fmac_f32_dpp v231, v77, v207 row_shr:1 row_mask:0xf bank_mask:0xf
	v_fmac_f32_dpp v232, v78, v208 row_shr:1 row_mask:0xf bank_mask:0xf
	v_fmac_f32_dpp v233, v79, v209 row_shr:1 row_mask:0xf bank_mask:0xf
	v_fmac_f32_dpp v234, v72, v210 row_shr:1 row_mask:0xf bank_mask:0xf
	v_fmac_f32_dpp v235, v73, v211 row_shr:1 row_mask:0xf bank_mask:0xf
	v_fmac_f32_dpp v236, v74, v212 row_shr:1 row_mask:0xf bank_mask:0xf
	v_fmac_f32_dpp v237, v75, v213 row_shr:1 row_mask:0xf bank_mask:0xf
	v_fmac_f32_dpp v230, v76, v198 row_shr:2 row_mask:0xf bank_mask:0xf
	v_fmac_f32_dpp v231, v77, v199 row_shr:2 row_mask:0xf bank_mask:0xf
	v_fmac_f32_dpp v232, v78, v200 row_shr:2 row_mask:0xf bank_mask:0xf
	v_fmac_f32_dpp v233, v79, v201 row_shr:2 row_mask:0xf bank_mask:0xf
	v_fmac_f32_dpp v234, v72, v202 row_shr:2 row_mask:0xf bank_mask:0xf
	v_fmac_f32_dpp v235, v73, v203 row_shr:2 row_mask:0xf bank_mask:0xf
	v_fmac_f32_dpp v236, v74, v204 row_shr:2 row_mask:0xf bank_mask:0xf
	v_fmac_f32_dpp v237, v75, v205 row_shr:2 row_mask:0xf bank_mask:0xf
	v_fmac_f32_dpp v230, v84, v206 row_shl:15 row_mask:0xf bank_mask:0xf
	v_fmac_f32_dpp v231, v85, v207 row_shl:15 row_mask:0xf bank_mask:0xf
	v_fmac_f32_dpp v232, v86, v208 row_shl:15 row_mask:0xf bank_mask:0xf
	v_fmac_f32_dpp v233, v87, v209 row_shl:15 row_mask:0xf bank_mask:0xf
	v_fmac_f32_dpp v234, v80, v210 row_shl:15 row_mask:0xf bank_mask:0xf
	v_fmac_f32_dpp v235, v81, v211 row_shl:15 row_mask:0xf bank_mask:0xf
	v_fmac_f32_dpp v236, v82, v212 row_shl:15 row_mask:0xf bank_mask:0xf
	v_fmac_f32_dpp v237, v83, v213 row_shl:15 row_mask:0xf bank_mask:0xf
	v_fmac_f32_dpp v230, v84, v198 row_shl:14 row_mask:0xf bank_mask:0xf
	v_fmac_f32_dpp v231, v85, v199 row_shl:14 row_mask:0xf bank_mask:0xf
	v_fmac_f32_dpp v232, v86, v200 row_shl:14 row_mask:0xf bank_mask:0xf
	v_fmac_f32_dpp v233, v87, v201 row_shl:14 row_mask:0xf bank_mask:0xf
	v_fmac_f32_dpp v234, v80, v202 row_shl:14 row_mask:0xf bank_mask:0xf
	v_fmac_f32_dpp v235, v81, v203 row_shl:14 row_mask:0xf bank_mask:0xf
	v_fmac_f32_dpp v236, v82, v204 row_shl:14 row_mask:0xf bank_mask:0xf
	v_fmac_f32_dpp v237, v83, v205 row_shl:14 row_mask:0xf bank_mask:0xf
	v_pk_mul_f32 v[238:239], v[230:231], v[230:231]
	v_pk_mul_f32 v[240:241], v[232:233], v[232:233]
	v_pk_fma_f32 v[238:239], v[238:239], v[248:249], v[246:247]
	v_pk_fma_f32 v[240:241], v[240:241], v[248:249], v[246:247]
	v_pk_mul_f32 v[238:239], v[230:231], v[238:239]
	v_pk_mul_f32 v[240:241], v[232:233], v[240:241]
	v_exp_f32_e32 v238, v238
	v_exp_f32_e32 v239, v239
	v_exp_f32_e32 v240, v240
	v_exp_f32_e32 v241, v241
	v_pk_add_f32 v[238:239], v[238:239], 1.0 op_sel_hi:[1,0]
	v_pk_add_f32 v[240:241], v[240:241], 1.0 op_sel_hi:[1,0]
	v_rcp_f32_e32 v238, v238
	v_rcp_f32_e32 v239, v239
	v_rcp_f32_e32 v240, v240
	v_rcp_f32_e32 v241, v241
	v_pk_mul_f32 v[230:231], v[230:231], v[234:235]
	v_pk_mul_f32 v[232:233], v[232:233], v[236:237]
	v_pk_mul_f32 v[238:239], v[230:231], v[238:239]
	v_pk_mul_f32 v[240:241], v[232:233], v[240:241]
	v_cvt_pk_bf16_f32 v176, v238, v239
	v_cvt_pk_bf16_f32 v177, v240, v241
	v_pk_fma_f32 v[230:231], v[12:13], v[128:129], v[100:101]
	v_pk_fma_f32 v[234:235], v[8:9], v[132:133], v[104:105]
	v_pk_fma_f32 v[232:233], v[14:15], v[130:131], v[102:103]
	v_pk_fma_f32 v[236:237], v[10:11], v[134:135], v[106:107]
	v_fmac_f32_dpp v230, v12, v120 row_shr:1 row_mask:0xf bank_mask:0xf
	v_fmac_f32_dpp v231, v13, v121 row_shr:1 row_mask:0xf bank_mask:0xf
	v_fmac_f32_dpp v232, v14, v122 row_shr:1 row_mask:0xf bank_mask:0xf
	v_fmac_f32_dpp v233, v15, v123 row_shr:1 row_mask:0xf bank_mask:0xf
	v_fmac_f32_dpp v234, v8, v124 row_shr:1 row_mask:0xf bank_mask:0xf
	v_fmac_f32_dpp v235, v9, v125 row_shr:1 row_mask:0xf bank_mask:0xf
	v_fmac_f32_dpp v236, v10, v126 row_shr:1 row_mask:0xf bank_mask:0xf
	v_fmac_f32_dpp v237, v11, v127 row_shr:1 row_mask:0xf bank_mask:0xf
	v_fmac_f32_dpp v230, v12, v112 row_shr:2 row_mask:0xf bank_mask:0xf
	v_fmac_f32_dpp v231, v13, v113 row_shr:2 row_mask:0xf bank_mask:0xf
	v_fmac_f32_dpp v232, v14, v114 row_shr:2 row_mask:0xf bank_mask:0xf
	v_fmac_f32_dpp v233, v15, v115 row_shr:2 row_mask:0xf bank_mask:0xf
	v_fmac_f32_dpp v234, v8, v116 row_shr:2 row_mask:0xf bank_mask:0xf
	v_fmac_f32_dpp v235, v9, v117 row_shr:2 row_mask:0xf bank_mask:0xf
	v_fmac_f32_dpp v236, v10, v118 row_shr:2 row_mask:0xf bank_mask:0xf
	v_fmac_f32_dpp v237, v11, v119 row_shr:2 row_mask:0xf bank_mask:0xf
	v_fmac_f32_dpp v230, v20, v120 row_shl:15 row_mask:0xf bank_mask:0xf
	v_fmac_f32_dpp v231, v21, v121 row_shl:15 row_mask:0xf bank_mask:0xf
	v_fmac_f32_dpp v232, v22, v122 row_shl:15 row_mask:0xf bank_mask:0xf
	v_fmac_f32_dpp v233, v23, v123 row_shl:15 row_mask:0xf bank_mask:0xf
	v_fmac_f32_dpp v234, v16, v124 row_shl:15 row_mask:0xf bank_mask:0xf
	v_fmac_f32_dpp v235, v17, v125 row_shl:15 row_mask:0xf bank_mask:0xf
	v_fmac_f32_dpp v236, v18, v126 row_shl:15 row_mask:0xf bank_mask:0xf
	v_fmac_f32_dpp v237, v19, v127 row_shl:15 row_mask:0xf bank_mask:0xf
	v_fmac_f32_dpp v230, v20, v112 row_shl:14 row_mask:0xf bank_mask:0xf
	v_fmac_f32_dpp v231, v21, v113 row_shl:14 row_mask:0xf bank_mask:0xf
	v_fmac_f32_dpp v232, v22, v114 row_shl:14 row_mask:0xf bank_mask:0xf
	v_fmac_f32_dpp v233, v23, v115 row_shl:14 row_mask:0xf bank_mask:0xf
	v_fmac_f32_dpp v234, v16, v116 row_shl:14 row_mask:0xf bank_mask:0xf
	v_fmac_f32_dpp v235, v17, v117 row_shl:14 row_mask:0xf bank_mask:0xf
	v_fmac_f32_dpp v236, v18, v118 row_shl:14 row_mask:0xf bank_mask:0xf
	v_fmac_f32_dpp v237, v19, v119 row_shl:14 row_mask:0xf bank_mask:0xf
	v_pk_mul_f32 v[238:239], v[230:231], v[230:231]
	v_pk_mul_f32 v[240:241], v[232:233], v[232:233]
	v_pk_fma_f32 v[238:239], v[238:239], v[248:249], v[246:247]
	v_pk_fma_f32 v[240:241], v[240:241], v[248:249], v[246:247]
	v_pk_mul_f32 v[238:239], v[230:231], v[238:239]
	v_pk_mul_f32 v[240:241], v[232:233], v[240:241]
	v_exp_f32_e32 v238, v238
	v_exp_f32_e32 v239, v239
	v_exp_f32_e32 v240, v240
	v_exp_f32_e32 v241, v241
	v_pk_add_f32 v[238:239], v[238:239], 1.0 op_sel_hi:[1,0]
	v_pk_add_f32 v[240:241], v[240:241], 1.0 op_sel_hi:[1,0]
	v_rcp_f32_e32 v238, v238
	v_rcp_f32_e32 v239, v239
	v_rcp_f32_e32 v240, v240
	v_rcp_f32_e32 v241, v241
	v_pk_mul_f32 v[230:231], v[230:231], v[234:235]
	v_pk_mul_f32 v[232:233], v[232:233], v[236:237]
	v_pk_mul_f32 v[238:239], v[230:231], v[238:239]
	v_pk_mul_f32 v[240:241], v[232:233], v[240:241]
	v_cvt_pk_bf16_f32 v178, v238, v239
	v_cvt_pk_bf16_f32 v179, v240, v241
	s_movk_i32 s15, 0xf66
	v_cmp_gt_i32_e64 s[24:25], s15, v251
	s_add_u32 s84, s58, 0xd3c00
	s_addc_u32 s85, s59, 0
	s_mov_b64 exec, s[24:25]
	global_store_dwordx4 v250, v[176:179], s[84:85]
	s_mov_b64 exec, -1
	s_nop 1
	v_pk_fma_f32 v[230:231], v[68:69], v[214:215], v[222:223]
	v_pk_fma_f32 v[234:235], v[64:65], v[218:219], v[226:227]
	v_pk_fma_f32 v[232:233], v[70:71], v[216:217], v[224:225]
	v_pk_fma_f32 v[236:237], v[66:67], v[220:221], v[228:229]
	v_fmac_f32_dpp v230, v68, v206 row_shr:1 row_mask:0xf bank_mask:0xf
	v_fmac_f32_dpp v231, v69, v207 row_shr:1 row_mask:0xf bank_mask:0xf
	v_fmac_f32_dpp v232, v70, v208 row_shr:1 row_mask:0xf bank_mask:0xf
	v_fmac_f32_dpp v233, v71, v209 row_shr:1 row_mask:0xf bank_mask:0xf
	v_fmac_f32_dpp v234, v64, v210 row_shr:1 row_mask:0xf bank_mask:0xf
	v_fmac_f32_dpp v235, v65, v211 row_shr:1 row_mask:0xf bank_mask:0xf
	v_fmac_f32_dpp v236, v66, v212 row_shr:1 row_mask:0xf bank_mask:0xf
	v_fmac_f32_dpp v237, v67, v213 row_shr:1 row_mask:0xf bank_mask:0xf
	v_fmac_f32_dpp v230, v68, v198 row_shr:2 row_mask:0xf bank_mask:0xf
	v_fmac_f32_dpp v231, v69, v199 row_shr:2 row_mask:0xf bank_mask:0xf
	v_fmac_f32_dpp v232, v70, v200 row_shr:2 row_mask:0xf bank_mask:0xf
	v_fmac_f32_dpp v233, v71, v201 row_shr:2 row_mask:0xf bank_mask:0xf
	v_fmac_f32_dpp v234, v64, v202 row_shr:2 row_mask:0xf bank_mask:0xf
	v_fmac_f32_dpp v235, v65, v203 row_shr:2 row_mask:0xf bank_mask:0xf
	v_fmac_f32_dpp v236, v66, v204 row_shr:2 row_mask:0xf bank_mask:0xf
	v_fmac_f32_dpp v237, v67, v205 row_shr:2 row_mask:0xf bank_mask:0xf
	v_fmac_f32_dpp v230, v76, v206 row_shl:15 row_mask:0xf bank_mask:0xf
	v_fmac_f32_dpp v231, v77, v207 row_shl:15 row_mask:0xf bank_mask:0xf
	v_fmac_f32_dpp v232, v78, v208 row_shl:15 row_mask:0xf bank_mask:0xf
	v_fmac_f32_dpp v233, v79, v209 row_shl:15 row_mask:0xf bank_mask:0xf
	v_fmac_f32_dpp v234, v72, v210 row_shl:15 row_mask:0xf bank_mask:0xf
	v_fmac_f32_dpp v235, v73, v211 row_shl:15 row_mask:0xf bank_mask:0xf
	v_fmac_f32_dpp v236, v74, v212 row_shl:15 row_mask:0xf bank_mask:0xf
	v_fmac_f32_dpp v237, v75, v213 row_shl:15 row_mask:0xf bank_mask:0xf
	v_fmac_f32_dpp v230, v76, v198 row_shl:14 row_mask:0xf bank_mask:0xf
	v_fmac_f32_dpp v231, v77, v199 row_shl:14 row_mask:0xf bank_mask:0xf
	v_fmac_f32_dpp v232, v78, v200 row_shl:14 row_mask:0xf bank_mask:0xf
	v_fmac_f32_dpp v233, v79, v201 row_shl:14 row_mask:0xf bank_mask:0xf
	v_fmac_f32_dpp v234, v72, v202 row_shl:14 row_mask:0xf bank_mask:0xf
	v_fmac_f32_dpp v235, v73, v203 row_shl:14 row_mask:0xf bank_mask:0xf
	v_fmac_f32_dpp v236, v74, v204 row_shl:14 row_mask:0xf bank_mask:0xf
	v_fmac_f32_dpp v237, v75, v205 row_shl:14 row_mask:0xf bank_mask:0xf
	v_pk_mul_f32 v[238:239], v[230:231], v[230:231]
	v_pk_mul_f32 v[240:241], v[232:233], v[232:233]
	v_pk_fma_f32 v[238:239], v[238:239], v[248:249], v[246:247]
	v_pk_fma_f32 v[240:241], v[240:241], v[248:249], v[246:247]
	v_pk_mul_f32 v[238:239], v[230:231], v[238:239]
	v_pk_mul_f32 v[240:241], v[232:233], v[240:241]
	v_exp_f32_e32 v238, v238
	v_exp_f32_e32 v239, v239
	v_exp_f32_e32 v240, v240
	v_exp_f32_e32 v241, v241
	v_pk_add_f32 v[238:239], v[238:239], 1.0 op_sel_hi:[1,0]
	v_pk_add_f32 v[240:241], v[240:241], 1.0 op_sel_hi:[1,0]
	v_rcp_f32_e32 v238, v238
	v_rcp_f32_e32 v239, v239
	v_rcp_f32_e32 v240, v240
	v_rcp_f32_e32 v241, v241
	v_pk_mul_f32 v[230:231], v[230:231], v[234:235]
	v_pk_mul_f32 v[232:233], v[232:233], v[236:237]
	v_pk_mul_f32 v[238:239], v[230:231], v[238:239]
	v_pk_mul_f32 v[240:241], v[232:233], v[240:241]
	v_cvt_pk_bf16_f32 v180, v238, v239
	v_cvt_pk_bf16_f32 v181, v240, v241
	v_pk_fma_f32 v[230:231], v[4:5], v[128:129], v[100:101]
	v_pk_fma_f32 v[234:235], v[0:1], v[132:133], v[104:105]
	v_pk_fma_f32 v[232:233], v[6:7], v[130:131], v[102:103]
	v_pk_fma_f32 v[236:237], v[2:3], v[134:135], v[106:107]
	v_fmac_f32_dpp v230, v4, v120 row_shr:1 row_mask:0xf bank_mask:0xf
	v_fmac_f32_dpp v231, v5, v121 row_shr:1 row_mask:0xf bank_mask:0xf
	v_fmac_f32_dpp v232, v6, v122 row_shr:1 row_mask:0xf bank_mask:0xf
	v_fmac_f32_dpp v233, v7, v123 row_shr:1 row_mask:0xf bank_mask:0xf
	v_fmac_f32_dpp v234, v0, v124 row_shr:1 row_mask:0xf bank_mask:0xf
	v_fmac_f32_dpp v235, v1, v125 row_shr:1 row_mask:0xf bank_mask:0xf
	v_fmac_f32_dpp v236, v2, v126 row_shr:1 row_mask:0xf bank_mask:0xf
	v_fmac_f32_dpp v237, v3, v127 row_shr:1 row_mask:0xf bank_mask:0xf
	v_fmac_f32_dpp v230, v4, v112 row_shr:2 row_mask:0xf bank_mask:0xf
	v_fmac_f32_dpp v231, v5, v113 row_shr:2 row_mask:0xf bank_mask:0xf
	v_fmac_f32_dpp v232, v6, v114 row_shr:2 row_mask:0xf bank_mask:0xf
	v_fmac_f32_dpp v233, v7, v115 row_shr:2 row_mask:0xf bank_mask:0xf
	v_fmac_f32_dpp v234, v0, v116 row_shr:2 row_mask:0xf bank_mask:0xf
	v_fmac_f32_dpp v235, v1, v117 row_shr:2 row_mask:0xf bank_mask:0xf
	v_fmac_f32_dpp v236, v2, v118 row_shr:2 row_mask:0xf bank_mask:0xf
	v_fmac_f32_dpp v237, v3, v119 row_shr:2 row_mask:0xf bank_mask:0xf
	v_fmac_f32_dpp v230, v12, v120 row_shl:15 row_mask:0xf bank_mask:0xf
	v_fmac_f32_dpp v231, v13, v121 row_shl:15 row_mask:0xf bank_mask:0xf
	v_fmac_f32_dpp v232, v14, v122 row_shl:15 row_mask:0xf bank_mask:0xf
	v_fmac_f32_dpp v233, v15, v123 row_shl:15 row_mask:0xf bank_mask:0xf
	v_fmac_f32_dpp v234, v8, v124 row_shl:15 row_mask:0xf bank_mask:0xf
	v_fmac_f32_dpp v235, v9, v125 row_shl:15 row_mask:0xf bank_mask:0xf
	v_fmac_f32_dpp v236, v10, v126 row_shl:15 row_mask:0xf bank_mask:0xf
	v_fmac_f32_dpp v237, v11, v127 row_shl:15 row_mask:0xf bank_mask:0xf
	v_fmac_f32_dpp v230, v12, v112 row_shl:14 row_mask:0xf bank_mask:0xf
	v_fmac_f32_dpp v231, v13, v113 row_shl:14 row_mask:0xf bank_mask:0xf
	v_fmac_f32_dpp v232, v14, v114 row_shl:14 row_mask:0xf bank_mask:0xf
	v_fmac_f32_dpp v233, v15, v115 row_shl:14 row_mask:0xf bank_mask:0xf
	v_fmac_f32_dpp v234, v8, v116 row_shl:14 row_mask:0xf bank_mask:0xf
	v_fmac_f32_dpp v235, v9, v117 row_shl:14 row_mask:0xf bank_mask:0xf
	v_fmac_f32_dpp v236, v10, v118 row_shl:14 row_mask:0xf bank_mask:0xf
	v_fmac_f32_dpp v237, v11, v119 row_shl:14 row_mask:0xf bank_mask:0xf
	v_pk_mul_f32 v[238:239], v[230:231], v[230:231]
	v_pk_mul_f32 v[240:241], v[232:233], v[232:233]
	v_pk_fma_f32 v[238:239], v[238:239], v[248:249], v[246:247]
	v_pk_fma_f32 v[240:241], v[240:241], v[248:249], v[246:247]
	v_pk_mul_f32 v[238:239], v[230:231], v[238:239]
	v_pk_mul_f32 v[240:241], v[232:233], v[240:241]
	v_exp_f32_e32 v238, v238
	v_exp_f32_e32 v239, v239
	v_exp_f32_e32 v240, v240
	v_exp_f32_e32 v241, v241
	v_pk_add_f32 v[238:239], v[238:239], 1.0 op_sel_hi:[1,0]
	v_pk_add_f32 v[240:241], v[240:241], 1.0 op_sel_hi:[1,0]
	v_rcp_f32_e32 v238, v238
	v_rcp_f32_e32 v239, v239
	v_rcp_f32_e32 v240, v240
	v_rcp_f32_e32 v241, v241
	v_pk_mul_f32 v[230:231], v[230:231], v[234:235]
	v_pk_mul_f32 v[232:233], v[232:233], v[236:237]
	v_pk_mul_f32 v[238:239], v[230:231], v[238:239]
	v_pk_mul_f32 v[240:241], v[232:233], v[240:241]
	v_cvt_pk_bf16_f32 v182, v238, v239
	v_cvt_pk_bf16_f32 v183, v240, v241
	s_movk_i32 s15, 0xf56
	v_cmp_gt_i32_e64 s[24:25], s15, v251
	s_add_u32 s84, s58, 0xe9c00
	s_addc_u32 s85, s59, 0
	s_mov_b64 exec, s[24:25]
	global_store_dwordx4 v250, v[180:183], s[84:85]
	s_mov_b64 exec, -1
	s_nop 1
	s_mov_b64 s[0:1], -1
